# wave all-reduces (m3 rmsnorm tail, phase-A rmsnorm) via DPP row ops + readlane instead of six ds_bpermute hops
# baseline (speedup 1.0000x reference)
.LBB0_84:
	global_load_dwordx4 v[20:23], v[18:19], off offset:-3072
	global_load_dwordx4 v[24:27], v[18:19], off offset:-2048
	global_load_dwordx4 v[28:31], v[18:19], off offset:-1024
	global_load_dwordx4 v[32:35], v[18:19], off
	v_mov_b32_e32 v36, v201
	s_add_i32 s2, s2, s78
	v_lshlrev_b32_e32 v36, 2, v36
	v_xor_b32_e32 v47, 4, v36
	v_xor_b32_e32 v50, 8, v36
	v_xor_b32_e32 v51, 16, v36
	v_xor_b32_e32 v52, 32, v36
	v_xor_b32_e32 v53, 64, v36
	v_xor_b32_e32 v54, 0x80, v36
	v_lshl_add_u64 v[18:19], v[18:19], 0, s[6:7]
	s_cmpk_lt_i32 s2, 0x4000
	s_waitcnt vmcnt(3)
	v_pk_mul_f32 v[36:37], v[22:23], v[22:23]
	v_pk_mul_f32 v[38:39], v[20:21], v[20:21]
	s_waitcnt vmcnt(2)
	v_pk_mul_f32 v[40:41], v[26:27], v[26:27]
	v_pk_mul_f32 v[42:43], v[24:25], v[24:25]
	v_pk_mov_b32 v[48:49], v[38:39], v[36:37] op_sel:[1,0]
	v_mov_b32_e32 v39, v37
	v_pk_mov_b32 v[36:37], v[42:43], v[40:41] op_sel:[1,0]
	v_mov_b32_e32 v43, v41
	s_waitcnt vmcnt(1)
	v_mul_f32_e32 v44, v29, v29
	v_mul_f32_e32 v46, v31, v31
	v_pk_add_f32 v[38:39], v[48:49], v[38:39]
	v_pk_add_f32 v[36:37], v[36:37], v[42:43]
	s_waitcnt vmcnt(0)
	v_mul_f32_e32 v55, v32, v32
	v_mul_f32_e32 v56, v33, v33
	v_mul_f32_e32 v57, v34, v34
	v_mul_f32_e32 v58, v35, v35
	v_pk_fma_f32 v[40:41], v[28:29], v[28:29], v[44:45] op_sel_hi:[1,1,0]
	v_pk_fma_f32 v[44:45], v[30:31], v[30:31], v[46:47] op_sel_hi:[1,1,0]
	v_pk_add_f32 v[38:39], v[38:39], v[38:39] op_sel:[0,1] op_sel_hi:[1,0]
	v_pk_add_f32 v[36:37], v[36:37], v[36:37] op_sel:[0,1] op_sel_hi:[1,0]
	v_mov_b32_e32 v41, v57
	v_mov_b32_e32 v45, v58
	v_mov_b32_e32 v39, v55
	v_mov_b32_e32 v37, v56
	v_pk_add_f32 v[40:41], v[40:41], v[44:45]
	v_pk_add_f32 v[36:37], v[38:39], v[36:37]
	s_nop 0
	v_pk_add_f32 v[36:37], v[36:37], v[40:41]
	s_nop 0
	v_add_f32_e32 v36, v36, v37
	s_nop 1
	v_add_f32_dpp v37, v36, v36 quad_perm:[1,0,3,2] row_mask:0xf bank_mask:0xf
	s_nop 1
	v_add_f32_dpp v36, v37, v37 quad_perm:[2,3,0,1] row_mask:0xf bank_mask:0xf
	s_nop 1
	v_add_f32_dpp v37, v36, v36 row_half_mirror row_mask:0xf bank_mask:0xf
	s_nop 1
	v_add_f32_dpp v36, v37, v37 row_mirror row_mask:0xf bank_mask:0xf
	s_nop 1
	v_add_f32_dpp v36, v36, v36 row_bcast:15 row_mask:0xa bank_mask:0xf
	s_nop 1
	v_add_f32_dpp v36, v36, v36 row_bcast:31 row_mask:0xc bank_mask:0xf
	s_nop 1
	v_readlane_b32 s90, v36, 63
	s_nop 1
	v_mov_b32_e32 v36, s90
	v_fmamk_f32 v36, v36, 0x3a800000, v195
	v_mul_f32_e32 v37, 0x4b800000, v36
	v_cmp_gt_f32_e32 vcc, s67, v36
	s_nop 1
	v_cndmask_b32_e32 v36, v36, v37, vcc
	v_rsq_f32_e32 v36, v36
	s_nop 0
	v_mul_f32_e32 v37, 0x45800000, v36
	v_cndmask_b32_e32 v36, v36, v37, vcc
	v_pk_mul_f32 v[20:21], v[20:21], v[36:37] op_sel_hi:[1,0]
	v_pk_mul_f32 v[22:23], v[22:23], v[36:37] op_sel_hi:[1,0]
	v_pk_mul_f32 v[24:25], v[24:25], v[36:37] op_sel_hi:[1,0]
	v_pk_mul_f32 v[26:27], v[26:27], v[36:37] op_sel_hi:[1,0]
	v_pk_mul_f32 v[28:29], v[28:29], v[36:37] op_sel_hi:[1,0]
	v_pk_mul_f32 v[30:31], v[30:31], v[36:37] op_sel_hi:[1,0]
	v_pk_mul_f32 v[32:33], v[32:33], v[36:37] op_sel_hi:[1,0]
	v_pk_mul_f32 v[34:35], v[34:35], v[36:37] op_sel_hi:[1,0]
	v_pk_mul_f32 v[20:21], v[12:13], v[20:21]
	v_pk_mul_f32 v[22:23], v[14:15], v[22:23]
	v_pk_mul_f32 v[24:25], v[8:9], v[24:25]
	v_pk_mul_f32 v[26:27], v[10:11], v[26:27]
	v_pk_mul_f32 v[28:29], v[4:5], v[28:29]
	v_pk_mul_f32 v[30:31], v[6:7], v[30:31]
	v_pk_mul_f32 v[32:33], v[0:1], v[32:33]
	v_pk_mul_f32 v[34:35], v[2:3], v[34:35]
	v_cvt_pk_bf16_f32 v20, v20, v21
	v_cvt_pk_bf16_f32 v21, v22, v23
	v_cvt_pk_bf16_f32 v22, v24, v25
	v_cvt_pk_bf16_f32 v23, v26, v27
	v_cvt_pk_bf16_f32 v24, v28, v29
	v_cvt_pk_bf16_f32 v25, v30, v31
	v_cvt_pk_bf16_f32 v26, v32, v33
	v_cvt_pk_bf16_f32 v27, v34, v35
	global_store_dwordx2 v[16:17], v[20:21], off
	global_store_dwordx2 v[16:17], v[22:23], off offset:512
	global_store_dwordx2 v[16:17], v[24:25], off offset:1024
	global_store_dwordx2 v[16:17], v[26:27], off offset:1536
	v_lshl_add_u64 v[16:17], v[16:17], 0, s[4:5]
	s_cbranch_scc1 .LBB0_84

.LBB0_448:
	s_or_b64 exec, exec, s[2:3]
	v_bfe_u32 v3, v1, 16, 1
	s_movk_i32 s2, 0x7fff
	v_lshlrev_b32_e32 v2, 3, v4
	v_add3_u32 v1, v1, v3, s2
	ds_write_b16_d16_hi v0, v1 offset:60336
	v_mul_u32_u24_e32 v0, 0x90, v9
	v_lshlrev_b32_e32 v1, 1, v2
	s_waitcnt lgkmcnt(0)
	s_barrier
	v_add3_u32 v12, 0, v0, v1
	ds_read_b128 v[100:103], v10 offset:59904
	ds_read_b128 v[104:107], v10 offset:59968
	ds_read_b128 v[108:111], v10
	ds_read_b128 v[112:115], v10 offset:64
	ds_read_b128 v[14:17], v10 offset:59904
	ds_read_b128 v[0:3], v12 offset:36864
	ds_read_b128 v[18:21], v10 offset:59968
	ds_read_b128 v[4:7], v12 offset:36928
	s_waitcnt lgkmcnt(2)
	v_mfma_f32_16x16x32_bf16 v[0:3], v[14:17], v[0:3], 0
	s_lshl_b32 s2, s4, 2
	s_add_i32 s2, s2, 0
	s_add_i32 s2, s2, 0x19200
	s_waitcnt lgkmcnt(0)
	v_mfma_f32_16x16x32_bf16 v[24:27], v[18:21], v[4:7], v[0:3]
	ds_read_b128 v[28:31], v10
	s_nop 1
	ds_read_b128 v[0:3], v12 offset:57600
	ds_read_b128 v[32:35], v10 offset:64
	ds_read_b128 v[4:7], v12 offset:57664
	s_ashr_i32 s3, s40, 6
	s_waitcnt lgkmcnt(2)
	v_mfma_f32_16x16x32_bf16 v[0:3], v[28:31], v[0:3], 0
	v_readlane_b32 s7, v254, 34
	s_waitcnt lgkmcnt(0)
	v_mfma_f32_16x16x32_bf16 v[36:39], v[32:35], v[4:7], v[0:3]
	s_nop 4
	v_and_b32_e32 v0, 48, v23
	v_add_u32_e32 v4, s2, v0
	v_and_or_b32 v0, v201, 64, v0
	v_lshlrev_b32_e32 v12, 2, v0
	ds_read_b128 v[0:3], v4 offset:512
	ds_read_b128 v[4:7], v4 offset:768
	s_lshl_b32 s2, s3, 4
	s_and_b32 s6, s2, 0xffffffc0
	v_or_b32_e32 v40, s6, v9
	s_waitcnt lgkmcnt(1)
	v_fma_f32 v13, v36, v0, v24
	v_fma_f32 v23, v37, v1, v25
	v_fma_f32 v24, v38, v2, v26
	v_fmac_f32_e32 v27, v39, v3
	v_mad_u64_u32 v[36:37], s[4:5], v40, s84, v[8:9]
	v_mov_b32_e32 v116, v36
	ds_read_b128 v[120:123], v116 offset:20736
	ds_read_b128 v[124:127], v116 offset:20800
	ds_read_b128 v[128:131], v116 offset:41472
	ds_read_b128 v[132:135], v116 offset:41536
	ds_bpermute_b32 v38, v12, v24
	ds_bpermute_b32 v39, v12, v27
	ds_read_b128 v[24:27], v36 offset:18432
	s_waitcnt lgkmcnt(0)
	v_mfma_f32_16x16x32_bf16 v[14:17], v[14:17], v[24:27], 0
	ds_read_b128 v[24:27], v36 offset:18496
	ds_bpermute_b32 v13, v12, v13
	v_max_f32_e32 v4, v4, v4
	s_waitcnt lgkmcnt(1)
	v_mfma_f32_16x16x32_bf16 v[14:17], v[18:21], v[24:27], v[14:17]
	ds_read_b128 v[18:21], v36 offset:39168
	ds_read_b128 v[24:27], v36 offset:39232
	s_waitcnt lgkmcnt(2)
	v_max_f32_e64 v13, |v13|, |v13|
	s_waitcnt lgkmcnt(1)
	v_mfma_f32_16x16x32_bf16 v[18:21], v[28:31], v[18:21], 0
	v_max_f32_e32 v4, v13, v4
	ds_bpermute_b32 v23, v12, v23
	v_lshl_add_u32 v12, v9, 2, s7
	s_waitcnt lgkmcnt(1)
	v_mfma_f32_16x16x32_bf16 v[18:21], v[32:35], v[24:27], v[18:21]
	v_lshl_add_u32 v24, s6, 2, v12
	s_movk_i32 s6, 0x210
	v_mad_u32_u24 v36, v11, s6, v24
	v_max_f32_e32 v5, v5, v5
	v_max_f32_e32 v6, v6, v6
	s_nop 2
	v_fma_f32 v14, v0, v18, v14
	v_div_scale_f32 v13, s[4:5], v4, v4, v14
	v_rcp_f32_e32 v18, v13
	v_max_f32_e32 v7, v7, v7
	v_fmac_f32_e32 v17, v3, v21
	s_or_b32 s2, s2, 48
	v_fma_f32 v25, -v13, v18, 1.0
	v_fmac_f32_e32 v18, v25, v18
	v_div_scale_f32 v25, vcc, v14, v4, v14
	v_mul_f32_e32 v26, v25, v18
	v_fma_f32 v27, -v13, v26, v25
	v_fmac_f32_e32 v26, v27, v18
	v_fma_f32 v13, -v13, v26, v25
	v_div_fmas_f32 v13, v13, v18, v26
	v_div_fixup_f32 v13, v13, v4, v14
	s_waitcnt lgkmcnt(0)
	v_max_f32_e64 v14, |v23|, |v23|
	ds_write_b32 v36, v13
	v_fma_f32 v13, v1, v19, v15
	v_max_f32_e32 v5, v14, v5
	v_div_scale_f32 v14, s[4:5], v5, v5, v13
	v_rcp_f32_e32 v15, v14
	s_nop 0
	v_fma_f32 v18, -v14, v15, 1.0
	v_fmac_f32_e32 v15, v18, v15
	v_div_scale_f32 v18, vcc, v13, v5, v13
	v_mul_f32_e32 v19, v18, v15
	v_fma_f32 v23, -v14, v19, v18
	v_fmac_f32_e32 v19, v23, v15
	v_fma_f32 v14, -v14, v19, v18
	v_div_fmas_f32 v14, v14, v15, v19
	v_div_fixup_f32 v14, v14, v5, v13
	v_mad_u32_u24 v13, v11, s6, s6
	v_add_u32_e32 v23, v24, v13
	v_max_f32_e64 v15, |v38|, |v38|
	ds_write_b32 v23, v14
	v_fma_f32 v14, v2, v20, v16
	v_max_f32_e32 v6, v15, v6
	v_div_scale_f32 v15, s[4:5], v6, v6, v14
	v_rcp_f32_e32 v16, v15
	s_nop 0
	v_fma_f32 v18, -v15, v16, 1.0
	v_fmac_f32_e32 v16, v18, v16
	v_div_scale_f32 v18, vcc, v14, v6, v14
	v_mul_f32_e32 v19, v18, v16
	v_fma_f32 v20, -v15, v19, v18
	v_fmac_f32_e32 v19, v20, v16
	v_fma_f32 v15, -v15, v19, v18
	v_div_fmas_f32 v15, v15, v16, v19
	v_div_fixup_f32 v15, v15, v6, v14
	v_mov_b32_e32 v14, 0x420
	v_mad_u32_u24 v14, v11, s6, v14
	v_add_u32_e32 v37, v24, v14
	ds_write_b32 v37, v15
	v_max_f32_e64 v15, |v39|, |v39|
	v_max_f32_e32 v7, v15, v7
	v_div_scale_f32 v15, s[4:5], v7, v7, v17
	v_rcp_f32_e32 v16, v15
	s_nop 0
	v_fma_f32 v18, -v15, v16, 1.0
	v_fmac_f32_e32 v16, v18, v16
	v_div_scale_f32 v18, vcc, v17, v7, v17
	v_mul_f32_e32 v19, v18, v16
	v_fma_f32 v20, -v15, v19, v18
	v_fmac_f32_e32 v19, v20, v16
	v_fma_f32 v15, -v15, v19, v18
	v_div_fmas_f32 v15, v15, v16, v19
	v_div_fixup_f32 v16, v15, v7, v17
	v_mad_u32_u24 v15, v11, s6, v206
	v_add_u32_e32 v38, v24, v15
	ds_write_b32 v38, v16
	v_or_b32_e32 v16, 16, v40
	v_mad_u64_u32 v[20:21], s[4:5], v16, s84, v[8:9]
	s_waitcnt lgkmcnt(0)
	v_mfma_f32_16x16x32_bf16 v[16:19], v[100:103], v[120:123], 0
	v_mfma_f32_16x16x32_bf16 v[24:27], v[108:111], v[128:131], 0
	v_mfma_f32_16x16x32_bf16 v[16:19], v[104:107], v[124:127], v[16:19]
	v_mfma_f32_16x16x32_bf16 v[24:27], v[112:115], v[132:135], v[24:27]
	ds_read_b128 v[136:139], v116 offset:23040
	ds_read_b128 v[140:143], v116 offset:23104
	ds_read_b128 v[144:147], v116 offset:43776
	ds_read_b128 v[148:151], v116 offset:43840
	s_nop 7
	v_fma_f32 v16, v0, v24, v16
	v_div_scale_f32 v20, s[4:5], v4, v4, v16
	v_rcp_f32_e32 v21, v20
	v_fmac_f32_e32 v19, v3, v27
	v_fma_f32 v24, -v20, v21, 1.0
	v_fmac_f32_e32 v21, v24, v21
	v_div_scale_f32 v24, vcc, v16, v4, v16
	v_mul_f32_e32 v28, v24, v21
	v_fma_f32 v29, -v20, v28, v24
	v_fmac_f32_e32 v28, v29, v21
	v_fma_f32 v20, -v20, v28, v24
	v_div_fmas_f32 v20, v20, v21, v28
	v_div_fixup_f32 v16, v20, v4, v16
	ds_write_b32 v36, v16 offset:64
	v_fma_f32 v16, v1, v25, v17
	v_div_scale_f32 v17, s[4:5], v5, v5, v16
	v_rcp_f32_e32 v20, v17
	s_nop 0
	v_fma_f32 v21, -v17, v20, 1.0
	v_fmac_f32_e32 v20, v21, v20
	v_div_scale_f32 v21, vcc, v16, v5, v16
	v_mul_f32_e32 v24, v21, v20
	v_fma_f32 v25, -v17, v24, v21
	v_fmac_f32_e32 v24, v25, v20
	v_fma_f32 v17, -v17, v24, v21
	v_div_fmas_f32 v17, v17, v20, v24
	v_div_fixup_f32 v16, v17, v5, v16
	ds_write_b32 v23, v16 offset:64
	v_fma_f32 v16, v2, v26, v18
	v_div_scale_f32 v17, s[4:5], v6, v6, v16
	v_rcp_f32_e32 v18, v17
	s_nop 0
	v_fma_f32 v20, -v17, v18, 1.0
	v_fmac_f32_e32 v18, v20, v18
	v_div_scale_f32 v20, vcc, v16, v6, v16
	v_mul_f32_e32 v21, v20, v18
	v_fma_f32 v24, -v17, v21, v20
	v_fmac_f32_e32 v21, v24, v18
	v_fma_f32 v17, -v17, v21, v20
	v_div_fmas_f32 v17, v17, v18, v21
	v_div_fixup_f32 v16, v17, v6, v16
	ds_write_b32 v37, v16 offset:64
	v_div_scale_f32 v16, s[4:5], v7, v7, v19
	v_rcp_f32_e32 v17, v16
	s_nop 0
	v_fma_f32 v18, -v16, v17, 1.0
	v_fmac_f32_e32 v17, v18, v17
	v_div_scale_f32 v18, vcc, v19, v7, v19
	v_mul_f32_e32 v20, v18, v17
	v_fma_f32 v21, -v16, v20, v18
	v_fmac_f32_e32 v20, v21, v17
	v_fma_f32 v16, -v16, v20, v18
	v_div_fmas_f32 v16, v16, v17, v20
	v_div_fixup_f32 v16, v16, v7, v19
	ds_write_b32 v38, v16 offset:64
	v_or_b32_e32 v16, 32, v40
	v_mad_u64_u32 v[20:21], s[4:5], v16, s84, v[8:9]
	v_or_b32_e32 v9, s2, v9
	v_mad_u64_u32 v[8:9], s[4:5], v9, s84, v[8:9]
	s_waitcnt lgkmcnt(0)
	v_mfma_f32_16x16x32_bf16 v[16:19], v[100:103], v[136:139], 0
	v_mfma_f32_16x16x32_bf16 v[24:27], v[108:111], v[144:147], 0
	v_mfma_f32_16x16x32_bf16 v[16:19], v[104:107], v[140:143], v[16:19]
	v_mfma_f32_16x16x32_bf16 v[24:27], v[112:115], v[148:151], v[24:27]
	ds_read_b128 v[120:123], v116 offset:25344
	ds_read_b128 v[124:127], v116 offset:25408
	ds_read_b128 v[128:131], v116 offset:46080
	ds_read_b128 v[132:135], v116 offset:46144
	s_nop 7
	v_fma_f32 v16, v0, v24, v16
	v_div_scale_f32 v20, s[4:5], v4, v4, v16
	v_rcp_f32_e32 v21, v20
	v_fmac_f32_e32 v19, v3, v27
	v_fma_f32 v24, -v20, v21, 1.0
	v_fmac_f32_e32 v21, v24, v21
	v_div_scale_f32 v24, vcc, v16, v4, v16
	v_mul_f32_e32 v28, v24, v21
	v_fma_f32 v29, -v20, v28, v24
	v_fmac_f32_e32 v28, v29, v21
	v_fma_f32 v20, -v20, v28, v24
	v_div_fmas_f32 v20, v20, v21, v28
	v_div_fixup_f32 v16, v20, v4, v16
	ds_write_b32 v36, v16 offset:128
	v_fma_f32 v16, v1, v25, v17
	v_div_scale_f32 v17, s[4:5], v5, v5, v16
	v_rcp_f32_e32 v20, v17
	s_nop 0
	v_fma_f32 v21, -v17, v20, 1.0
	v_fmac_f32_e32 v20, v21, v20
	v_div_scale_f32 v21, vcc, v16, v5, v16
	v_mul_f32_e32 v24, v21, v20
	v_fma_f32 v25, -v17, v24, v21
	v_fmac_f32_e32 v24, v25, v20
	v_fma_f32 v17, -v17, v24, v21
	v_div_fmas_f32 v17, v17, v20, v24
	v_div_fixup_f32 v16, v17, v5, v16
	ds_write_b32 v23, v16 offset:128
	v_fma_f32 v16, v2, v26, v18
	v_div_scale_f32 v17, s[4:5], v6, v6, v16
	v_rcp_f32_e32 v18, v17
	s_nop 0
	v_fma_f32 v20, -v17, v18, 1.0
	v_fmac_f32_e32 v18, v20, v18
	v_div_scale_f32 v20, vcc, v16, v6, v16
	v_mul_f32_e32 v21, v20, v18
	v_fma_f32 v23, -v17, v21, v20
	v_fmac_f32_e32 v21, v23, v18
	v_fma_f32 v17, -v17, v21, v20
	v_div_fmas_f32 v17, v17, v18, v21
	v_div_fixup_f32 v16, v17, v6, v16
	ds_write_b32 v37, v16 offset:128
	v_div_scale_f32 v16, s[4:5], v7, v7, v19
	v_rcp_f32_e32 v17, v16
	s_nop 0
	v_fma_f32 v18, -v16, v17, 1.0
	v_fmac_f32_e32 v17, v18, v17
	v_div_scale_f32 v18, vcc, v19, v7, v19
	v_mul_f32_e32 v20, v18, v17
	v_fma_f32 v21, -v16, v20, v18
	v_fmac_f32_e32 v20, v21, v17
	v_fma_f32 v16, -v16, v20, v18
	v_div_fmas_f32 v16, v16, v17, v20
	v_div_fixup_f32 v16, v16, v7, v19
	ds_write_b32 v38, v16 offset:128
	v_lshl_add_u32 v8, s2, 2, v12
	s_lshl_b32 s2, s3, 3
	s_waitcnt lgkmcnt(0)
	v_mfma_f32_16x16x32_bf16 v[16:19], v[100:103], v[120:123], 0
	v_mfma_f32_16x16x32_bf16 v[24:27], v[108:111], v[128:131], 0
	v_mfma_f32_16x16x32_bf16 v[16:19], v[104:107], v[124:127], v[16:19]
	v_mfma_f32_16x16x32_bf16 v[24:27], v[112:115], v[132:135], v[24:27]
	s_mulk_i32 s3, 0x1080
	s_nop 6
	v_fma_f32 v0, v0, v24, v16
	v_div_scale_f32 v9, s[4:5], v4, v4, v0
	v_rcp_f32_e32 v10, v9
	v_fmac_f32_e32 v19, v3, v27
	v_fma_f32 v12, -v9, v10, 1.0
	v_fmac_f32_e32 v10, v12, v10
	v_div_scale_f32 v12, vcc, v0, v4, v0
	v_mul_f32_e32 v16, v12, v10
	v_fma_f32 v20, -v9, v16, v12
	v_fmac_f32_e32 v16, v20, v10
	v_fma_f32 v9, -v9, v16, v12
	v_div_fmas_f32 v9, v9, v10, v16
	v_div_fixup_f32 v0, v9, v4, v0
	v_mad_u32_u24 v4, v11, s6, v8
	ds_write_b32 v4, v0
	v_fma_f32 v0, v1, v25, v17
	v_div_scale_f32 v1, s[4:5], v5, v5, v0
	v_rcp_f32_e32 v4, v1
	s_nop 0
	v_fma_f32 v9, -v1, v4, 1.0
	v_fmac_f32_e32 v4, v9, v4
	v_div_scale_f32 v9, vcc, v0, v5, v0
	v_mul_f32_e32 v10, v9, v4
	v_fma_f32 v11, -v1, v10, v9
	v_fmac_f32_e32 v10, v11, v4
	v_fma_f32 v1, -v1, v10, v9
	v_div_fmas_f32 v1, v1, v4, v10
	v_div_fixup_f32 v0, v1, v5, v0
	v_add_u32_e32 v1, v8, v13
	ds_write_b32 v1, v0
	v_fma_f32 v0, v2, v26, v18
	v_div_scale_f32 v1, s[4:5], v6, v6, v0
	v_rcp_f32_e32 v2, v1
	s_nop 0
	v_fma_f32 v4, -v1, v2, 1.0
	v_fmac_f32_e32 v2, v4, v2
	v_div_scale_f32 v4, vcc, v0, v6, v0
	v_mul_f32_e32 v5, v4, v2
	v_fma_f32 v9, -v1, v5, v4
	v_fmac_f32_e32 v5, v9, v2
	v_fma_f32 v1, -v1, v5, v4
	v_div_fmas_f32 v1, v1, v2, v5
	v_div_fixup_f32 v0, v1, v6, v0
	v_add_u32_e32 v1, v8, v14
	ds_write_b32 v1, v0
	v_div_scale_f32 v0, s[4:5], v7, v7, v19
	v_rcp_f32_e32 v1, v0
	s_nop 0
	v_fma_f32 v2, -v0, v1, 1.0
	v_fmac_f32_e32 v1, v2, v1
	v_div_scale_f32 v2, vcc, v19, v7, v19
	v_mul_f32_e32 v3, v2, v1
	v_fma_f32 v4, -v0, v3, v2
	v_fmac_f32_e32 v3, v4, v1
	v_fma_f32 v0, -v0, v3, v2
	v_lshlrev_b32_e32 v2, 3, v22
	v_div_fmas_f32 v0, v0, v1, v3
	v_add_u32_e32 v10, s7, v2
	v_div_fixup_f32 v0, v0, v7, v19
	v_add_u32_e32 v1, v8, v15
	v_add_u32_e32 v6, s3, v10
	ds_write_b32 v1, v0
	s_waitcnt lgkmcnt(0)
	s_barrier
	s_add_u32 s4, s34, s2
	s_addc_u32 s5, s35, 0
	s_lshl_b64 s[4:5], s[4:5], 11
	s_lshl_b32 s3, s12, 1
	v_lshl_or_b32 v3, v22, 2, s3
	ds_read_b64 v[48:49], v6
	ds_read_b64 v[50:51], v6 offset:528
	ds_read_b64 v[52:53], v6 offset:1056
	ds_read_b64 v[54:55], v6 offset:1584
	ds_read_b64 v[56:57], v6 offset:2112
	ds_read_b64 v[58:59], v6 offset:2640
	ds_read_b64 v[60:61], v6 offset:3168
	ds_read_b64 v[62:63], v6 offset:3696
	s_add_u32 s98, s24, s4
	s_addc_u32 s99, s25, s5
	v_lshlrev_b32_e32 v90, 2, v201
	v_xor_b32_e32 v91, 4, v90
	v_xor_b32_e32 v92, 8, v90
	v_xor_b32_e32 v93, 16, v90
	v_xor_b32_e32 v94, 32, v90
	v_xor_b32_e32 v95, 64, v90
	v_xor_b32_e32 v96, 0x80, v90
	s_waitcnt lgkmcnt(0)
	v_pk_mul_f32 v[98:99], v[48:49], v[48:49]
	v_add_f32_e32 v64, v98, v99
	v_pk_mul_f32 v[98:99], v[50:51], v[50:51]
	v_add_f32_e32 v65, v98, v99
	v_pk_mul_f32 v[98:99], v[52:53], v[52:53]
	v_add_f32_e32 v66, v98, v99
	v_pk_mul_f32 v[98:99], v[54:55], v[54:55]
	v_add_f32_e32 v67, v98, v99
	v_pk_mul_f32 v[98:99], v[56:57], v[56:57]
	v_add_f32_e32 v68, v98, v99
	v_pk_mul_f32 v[98:99], v[58:59], v[58:59]
	v_add_f32_e32 v69, v98, v99
	v_pk_mul_f32 v[98:99], v[60:61], v[60:61]
	v_add_f32_e32 v70, v98, v99
	v_pk_mul_f32 v[98:99], v[62:63], v[62:63]
	v_add_f32_e32 v71, v98, v99
	v_add_f32_dpp v72, v64, v64 quad_perm:[1,0,3,2] row_mask:0xf bank_mask:0xf
	v_add_f32_dpp v73, v65, v65 quad_perm:[1,0,3,2] row_mask:0xf bank_mask:0xf
	v_add_f32_dpp v74, v66, v66 quad_perm:[1,0,3,2] row_mask:0xf bank_mask:0xf
	v_add_f32_dpp v75, v67, v67 quad_perm:[1,0,3,2] row_mask:0xf bank_mask:0xf
	v_add_f32_dpp v76, v68, v68 quad_perm:[1,0,3,2] row_mask:0xf bank_mask:0xf
	v_add_f32_dpp v77, v69, v69 quad_perm:[1,0,3,2] row_mask:0xf bank_mask:0xf
	v_add_f32_dpp v78, v70, v70 quad_perm:[1,0,3,2] row_mask:0xf bank_mask:0xf
	v_add_f32_dpp v79, v71, v71 quad_perm:[1,0,3,2] row_mask:0xf bank_mask:0xf
	v_add_f32_dpp v64, v72, v72 quad_perm:[2,3,0,1] row_mask:0xf bank_mask:0xf
	v_add_f32_dpp v65, v73, v73 quad_perm:[2,3,0,1] row_mask:0xf bank_mask:0xf
	v_add_f32_dpp v66, v74, v74 quad_perm:[2,3,0,1] row_mask:0xf bank_mask:0xf
	v_add_f32_dpp v67, v75, v75 quad_perm:[2,3,0,1] row_mask:0xf bank_mask:0xf
	v_add_f32_dpp v68, v76, v76 quad_perm:[2,3,0,1] row_mask:0xf bank_mask:0xf
	v_add_f32_dpp v69, v77, v77 quad_perm:[2,3,0,1] row_mask:0xf bank_mask:0xf
	v_add_f32_dpp v70, v78, v78 quad_perm:[2,3,0,1] row_mask:0xf bank_mask:0xf
	v_add_f32_dpp v71, v79, v79 quad_perm:[2,3,0,1] row_mask:0xf bank_mask:0xf
	v_add_f32_dpp v72, v64, v64 row_half_mirror row_mask:0xf bank_mask:0xf
	v_add_f32_dpp v73, v65, v65 row_half_mirror row_mask:0xf bank_mask:0xf
	v_add_f32_dpp v74, v66, v66 row_half_mirror row_mask:0xf bank_mask:0xf
	v_add_f32_dpp v75, v67, v67 row_half_mirror row_mask:0xf bank_mask:0xf
	v_add_f32_dpp v76, v68, v68 row_half_mirror row_mask:0xf bank_mask:0xf
	v_add_f32_dpp v77, v69, v69 row_half_mirror row_mask:0xf bank_mask:0xf
	v_add_f32_dpp v78, v70, v70 row_half_mirror row_mask:0xf bank_mask:0xf
	v_add_f32_dpp v79, v71, v71 row_half_mirror row_mask:0xf bank_mask:0xf
	v_add_f32_dpp v64, v72, v72 row_mirror row_mask:0xf bank_mask:0xf
	v_add_f32_dpp v65, v73, v73 row_mirror row_mask:0xf bank_mask:0xf
	v_add_f32_dpp v66, v74, v74 row_mirror row_mask:0xf bank_mask:0xf
	v_add_f32_dpp v67, v75, v75 row_mirror row_mask:0xf bank_mask:0xf
	v_add_f32_dpp v68, v76, v76 row_mirror row_mask:0xf bank_mask:0xf
	v_add_f32_dpp v69, v77, v77 row_mirror row_mask:0xf bank_mask:0xf
	v_add_f32_dpp v70, v78, v78 row_mirror row_mask:0xf bank_mask:0xf
	v_add_f32_dpp v71, v79, v79 row_mirror row_mask:0xf bank_mask:0xf
	v_add_f32_dpp v64, v64, v64 row_bcast:15 row_mask:0xa bank_mask:0xf
	v_add_f32_dpp v65, v65, v65 row_bcast:15 row_mask:0xa bank_mask:0xf
	v_add_f32_dpp v66, v66, v66 row_bcast:15 row_mask:0xa bank_mask:0xf
	v_add_f32_dpp v67, v67, v67 row_bcast:15 row_mask:0xa bank_mask:0xf
	v_add_f32_dpp v68, v68, v68 row_bcast:15 row_mask:0xa bank_mask:0xf
	v_add_f32_dpp v69, v69, v69 row_bcast:15 row_mask:0xa bank_mask:0xf
	v_add_f32_dpp v70, v70, v70 row_bcast:15 row_mask:0xa bank_mask:0xf
	v_add_f32_dpp v71, v71, v71 row_bcast:15 row_mask:0xa bank_mask:0xf
	v_add_f32_dpp v64, v64, v64 row_bcast:31 row_mask:0xc bank_mask:0xf
	v_add_f32_dpp v65, v65, v65 row_bcast:31 row_mask:0xc bank_mask:0xf
	v_add_f32_dpp v66, v66, v66 row_bcast:31 row_mask:0xc bank_mask:0xf
	v_add_f32_dpp v67, v67, v67 row_bcast:31 row_mask:0xc bank_mask:0xf
	v_add_f32_dpp v68, v68, v68 row_bcast:31 row_mask:0xc bank_mask:0xf
	v_add_f32_dpp v69, v69, v69 row_bcast:31 row_mask:0xc bank_mask:0xf
	v_add_f32_dpp v70, v70, v70 row_bcast:31 row_mask:0xc bank_mask:0xf
	v_add_f32_dpp v71, v71, v71 row_bcast:31 row_mask:0xc bank_mask:0xf
	v_readlane_b32 s46, v64, 63
	v_readlane_b32 s47, v65, 63
	v_readlane_b32 s48, v66, 63
	v_readlane_b32 s49, v67, 63
	v_readlane_b32 s50, v68, 63
	v_readlane_b32 s51, v69, 63
	v_readlane_b32 s52, v70, 63
	v_readlane_b32 s53, v71, 63
	v_mov_b32_e32 v64, s46
	v_mov_b32_e32 v65, s47
	v_mov_b32_e32 v66, s48
	v_mov_b32_e32 v67, s49
	v_mov_b32_e32 v68, s50
	v_mov_b32_e32 v69, s51
	v_mov_b32_e32 v70, s52
	v_mov_b32_e32 v71, s53
	v_fmamk_f32 v64, v64, 0x3c000000, v195
	v_cmp_gt_f32_e32 vcc, s67, v64
	v_mul_f32_e32 v72, 0x4b800000, v64
	s_nop 0
	v_cndmask_b32_e32 v64, v64, v72, vcc
	v_rsq_f32_e32 v64, v64
	s_nop 0
	v_mul_f32_e32 v72, 0x45800000, v64
	v_cndmask_b32_e32 v64, v64, v72, vcc
	v_fmamk_f32 v65, v65, 0x3c000000, v195
	v_cmp_gt_f32_e32 vcc, s67, v65
	v_mul_f32_e32 v73, 0x4b800000, v65
	s_nop 0
	v_cndmask_b32_e32 v65, v65, v73, vcc
	v_rsq_f32_e32 v65, v65
	s_nop 0
	v_mul_f32_e32 v73, 0x45800000, v65
	v_cndmask_b32_e32 v65, v65, v73, vcc
	v_fmamk_f32 v66, v66, 0x3c000000, v195
	v_cmp_gt_f32_e32 vcc, s67, v66
	v_mul_f32_e32 v74, 0x4b800000, v66
	s_nop 0
	v_cndmask_b32_e32 v66, v66, v74, vcc
	v_rsq_f32_e32 v66, v66
	s_nop 0
	v_mul_f32_e32 v74, 0x45800000, v66
	v_cndmask_b32_e32 v66, v66, v74, vcc
	v_fmamk_f32 v67, v67, 0x3c000000, v195
	v_cmp_gt_f32_e32 vcc, s67, v67
	v_mul_f32_e32 v75, 0x4b800000, v67
	s_nop 0
	v_cndmask_b32_e32 v67, v67, v75, vcc
	v_rsq_f32_e32 v67, v67
	s_nop 0
	v_mul_f32_e32 v75, 0x45800000, v67
	v_cndmask_b32_e32 v67, v67, v75, vcc
	v_fmamk_f32 v68, v68, 0x3c000000, v195
	v_cmp_gt_f32_e32 vcc, s67, v68
	v_mul_f32_e32 v76, 0x4b800000, v68
	s_nop 0
	v_cndmask_b32_e32 v68, v68, v76, vcc
	v_rsq_f32_e32 v68, v68
	s_nop 0
	v_mul_f32_e32 v76, 0x45800000, v68
	v_cndmask_b32_e32 v68, v68, v76, vcc
	v_fmamk_f32 v69, v69, 0x3c000000, v195
	v_cmp_gt_f32_e32 vcc, s67, v69
	v_mul_f32_e32 v77, 0x4b800000, v69
	s_nop 0
	v_cndmask_b32_e32 v69, v69, v77, vcc
	v_rsq_f32_e32 v69, v69
	s_nop 0
	v_mul_f32_e32 v77, 0x45800000, v69
	v_cndmask_b32_e32 v69, v69, v77, vcc
	v_fmamk_f32 v70, v70, 0x3c000000, v195
	v_cmp_gt_f32_e32 vcc, s67, v70
	v_mul_f32_e32 v78, 0x4b800000, v70
	s_nop 0
	v_cndmask_b32_e32 v70, v70, v78, vcc
	v_rsq_f32_e32 v70, v70
	s_nop 0
	v_mul_f32_e32 v78, 0x45800000, v70
	v_cndmask_b32_e32 v70, v70, v78, vcc
	v_fmamk_f32 v71, v71, 0x3c000000, v195
	v_cmp_gt_f32_e32 vcc, s67, v71
	v_mul_f32_e32 v79, 0x4b800000, v71
	s_nop 0
	v_cndmask_b32_e32 v71, v71, v79, vcc
	v_rsq_f32_e32 v71, v71
	s_nop 0
	v_mul_f32_e32 v79, 0x45800000, v71
	v_cndmask_b32_e32 v71, v71, v79, vcc
	s_waitcnt vmcnt(0)
	v_mul_f32_e32 v48, v48, v64
	v_mul_f32_e32 v49, v49, v64
	v_pk_mul_f32 v[48:49], v[234:235], v[48:49]
	v_lshlrev_b32_e32 v72, 16, v224
	v_and_b32_e32 v224, 0xffff0000, v224
	v_mul_f32_e32 v48, v48, v72
	v_mul_f32_e32 v49, v49, v224
	v_cvt_pk_bf16_f32 v72, v48, v49
	global_store_dword v3, v72, s[98:99]
	v_mul_f32_e32 v50, v50, v65
	v_mul_f32_e32 v51, v51, v65
	v_pk_mul_f32 v[50:51], v[234:235], v[50:51]
	v_lshlrev_b32_e32 v73, 16, v225
	v_and_b32_e32 v225, 0xffff0000, v225
	v_mul_f32_e32 v50, v50, v73
	v_mul_f32_e32 v51, v51, v225
	v_cvt_pk_bf16_f32 v73, v50, v51
	global_store_dword v3, v73, s[98:99] offset:2048
	s_add_u32 s98, s98, 0x1000
	s_addc_u32 s99, s99, 0
	v_mul_f32_e32 v52, v52, v66
	v_mul_f32_e32 v53, v53, v66
	v_pk_mul_f32 v[52:53], v[234:235], v[52:53]
	v_lshlrev_b32_e32 v74, 16, v226
	v_and_b32_e32 v226, 0xffff0000, v226
	v_mul_f32_e32 v52, v52, v74
	v_mul_f32_e32 v53, v53, v226
	v_cvt_pk_bf16_f32 v74, v52, v53
	global_store_dword v3, v74, s[98:99]
	v_mul_f32_e32 v54, v54, v67
	v_mul_f32_e32 v55, v55, v67
	v_pk_mul_f32 v[54:55], v[234:235], v[54:55]
	v_lshlrev_b32_e32 v75, 16, v227
	v_and_b32_e32 v227, 0xffff0000, v227
	v_mul_f32_e32 v54, v54, v75
	v_mul_f32_e32 v55, v55, v227
	v_cvt_pk_bf16_f32 v75, v54, v55
	global_store_dword v3, v75, s[98:99] offset:2048
	s_add_u32 s98, s98, 0x1000
	s_addc_u32 s99, s99, 0
	v_mul_f32_e32 v56, v56, v68
	v_mul_f32_e32 v57, v57, v68
	v_pk_mul_f32 v[56:57], v[234:235], v[56:57]
	v_lshlrev_b32_e32 v76, 16, v228
	v_and_b32_e32 v228, 0xffff0000, v228
	v_mul_f32_e32 v56, v56, v76
	v_mul_f32_e32 v57, v57, v228
	v_cvt_pk_bf16_f32 v76, v56, v57
	global_store_dword v3, v76, s[98:99]
	v_mul_f32_e32 v58, v58, v69
	v_mul_f32_e32 v59, v59, v69
	v_pk_mul_f32 v[58:59], v[234:235], v[58:59]
	v_lshlrev_b32_e32 v77, 16, v229
	v_and_b32_e32 v229, 0xffff0000, v229
	v_mul_f32_e32 v58, v58, v77
	v_mul_f32_e32 v59, v59, v229
	v_cvt_pk_bf16_f32 v77, v58, v59
	global_store_dword v3, v77, s[98:99] offset:2048
	s_add_u32 s98, s98, 0x1000
	s_addc_u32 s99, s99, 0
	v_mul_f32_e32 v60, v60, v70
	v_mul_f32_e32 v61, v61, v70
	v_pk_mul_f32 v[60:61], v[234:235], v[60:61]
	v_lshlrev_b32_e32 v78, 16, v230
	v_and_b32_e32 v230, 0xffff0000, v230
	v_mul_f32_e32 v60, v60, v78
	v_mul_f32_e32 v61, v61, v230
	v_cvt_pk_bf16_f32 v78, v60, v61
	global_store_dword v3, v78, s[98:99]
	v_mul_f32_e32 v62, v62, v71
	v_mul_f32_e32 v63, v63, v71
	v_pk_mul_f32 v[62:63], v[234:235], v[62:63]
	v_lshlrev_b32_e32 v79, 16, v231
	v_and_b32_e32 v231, 0xffff0000, v231
	v_mul_f32_e32 v62, v62, v79
	v_mul_f32_e32 v63, v63, v231
	v_cvt_pk_bf16_f32 v79, v62, v63
	global_store_dword v3, v79, s[98:99] offset:2048
	s_add_i32 s39, s39, s71
	s_cmpk_gt_i32 s39, 0x7ff
	s_barrier
	s_cbranch_scc1 .LBB0_494
